# adds: scan phase C reuses the 8 Vn fragments phase B already holds (two MFMA orderings selected by wave half; 32 instead of 40 LDS fragment reads per wave and step)
# speedup vs baseline: 1.0022x; 1.0022x over previous
; #define LAS __attribute__((address_space(3)))
; __device__ __forceinline__ void gdn_scan_full(const bf16* CHUNK, const float* CD, bf16* OG, LAS unsigned char* lds, int item, int tid, int wave, int lane) {
;     const int d = item >> 5, b = (item >> 4) & 1, h = item & 15;
;     const int ql = lane & 15, gq = lane >> 4, mt = wave & 3, ng = wave >> 2;
;     LAS bf16* Sb = (LAS bf16*)lds;
;     LAS bf16* Vn = Sb + 128 * 136;
;     for (int e = tid; e < 128 * 136 / 2; e += NTHR) ((LAS unsigned*)Sb)[e] = 0u;
;     f32x4 S[8];
; #pragma unroll
;     for (int t = 0; t < 8; ++t) S[t] = (f32x4){0.f, 0.f, 0.f, 0.f};
;     const int jb0 = ((d * 2 + b) * 16 + h) * 64;
;     bf16* og = OG + (size_t)d * M * 2048 + (size_t)b * SEQ * 2048 + h * 128 + 64 * ng + ql;
;     bf16x8_t wf[4], qf[4], inf[2], kf[2]; unsigned short uu[16]; float cdv;
;     bf16x8_t wfn[4], qfn[4], infn[2], kfn[2]; unsigned short uun[16]; float cdn;
;     ...
;     GF_LOAD(0, wfn, qfn, infn, kfn, uun, cdn);
;     __syncthreads();
.LBB0_365:
	v_add_u32_e32 v1, 0x200, v1
	s_movk_i32 s14, 0x1fff
	v_cmp_lt_u32_e32 vcc, s14, v1
	ds_write_b32 v0, v145
	s_or_b64 s[0:1], vcc, s[0:1]
	v_add_u32_e32 v0, 0x800, v0
	s_andn2_b64 exec, exec, s[0:1]
	s_cbranch_execnz .LBB0_365
	s_or_b64 exec, exec, s[0:1]
	s_bfe_u32 s42, s37, 0x10004
	s_and_b32 s0, s37, 0xffffffe0
	s_lshl_b32 s16, s42, 4
	s_or_b32 s0, s0, s16
	s_and_b32 s1, s36, 15
	s_or_b32 s17, s0, s1
	s_lshl_b32 s0, s17, 6
	s_ashr_i32 s1, s0, 31
	s_lshl_b64 s[14:15], s[0:1], 2
	s_add_u32 s38, s14, 0x43c00004
	s_addc_u32 s39, s15, 0
	s_mul_hi_i32 s40, s0, 0x12000
	v_mad_i64_i32 v[178:179], s[14:15], s0, v204, v[156:157]
	v_mad_i64_i32 v[180:181], s[14:15], s0, v204, v[158:159]
	v_mad_i64_i32 v[182:183], s[14:15], s0, v204, v[160:161]
	v_mad_i64_i32 v[184:185], s[14:15], s0, v204, v[162:163]
	v_mad_i64_i32 v[188:189], s[0:1], s0, v204, v[166:167]
	s_and_b32 s0, s37, 0x3ffffe0
	s_and_b32 s43, s37, 15
	s_or_b32 s0, s16, s0
	s_ashr_i32 s14, s37, 5
	s_or_b32 s16, s0, s43
	s_lshl_b32 s0, s16, 6
	s_ashr_i32 s15, s14, 31
	s_mul_i32 s17, s17, 0x480000
	s_lshl_b64 s[14:15], s[14:15], 25
	s_ashr_i32 s1, s0, 31
	s_mul_i32 s16, s16, 0x480000
	v_or_b32_e32 v186, s17, v164
	v_or_b32_e32 v190, s17, v168
	s_mul_hi_i32 s17, s0, 0x12000
	s_add_u32 s16, s33, s16
	s_addc_u32 s17, s82, s17
	v_mov_b32_e32 v171, v145
	v_mov_b32_e32 v173, v145
	v_lshl_add_u64 v[0:1], s[16:17], 0, v[170:171]
	v_mov_b32_e32 v187, s40
	v_mov_b32_e32 v191, s40
	v_lshl_add_u64 v[0:1], v[0:1], 0, v[172:173]
	s_mov_b64 s[40:41], 0x4000
	v_lshl_add_u64 v[2:3], v[0:1], 0, s[40:41]
	s_mov_b64 s[40:41], 0x8000
	v_lshl_add_u64 v[4:5], v[0:1], 0, s[40:41]
	s_movk_i32 s40, 0x4000
	v_add_co_u32_e32 v6, vcc, s40, v0
	v_readlane_b32 s44, v253, 32
	s_nop 0
	v_addc_co_u32_e32 v7, vcc, 0, v1, vcc
	s_mov_b32 s41, 0x8000
	v_readlane_b32 s45, v253, 33
	s_add_u32 s14, s44, s14
	v_add_co_u32_e32 v0, vcc, s41, v0
	s_addc_u32 s15, s45, s15
	s_lshl_b32 s41, s42, 24
	v_addc_co_u32_e32 v1, vcc, 0, v1, vcc
	s_add_u32 s14, s14, s41
	v_mov_b32_e32 v175, v145
	global_load_dwordx4 v[24:27], v[6:7], off
	global_load_dwordx4 v[16:19], v[0:1], off
	global_load_dwordx4 v[28:31], v[2:3], off offset:64
	global_load_dwordx4 v[12:15], v[4:5], off offset:64
	global_load_dwordx4 v[36:39], v[2:3], off offset:128
	global_load_dwordx4 v[8:11], v[4:5], off offset:128
	global_load_dwordx4 v[32:35], v[2:3], off offset:192
	global_load_dwordx4 v[20:23], v[4:5], off offset:192
	s_addc_u32 s15, s15, 0
	s_lshl_b32 s41, s43, 8
	v_lshl_add_u64 v[0:1], s[16:17], 0, v[174:175]
	s_add_u32 s14, s14, s41
	v_lshl_add_u64 v[0:1], v[0:1], 0, v[172:173]
	s_mov_b64 s[42:43], 0x10000
	s_mov_b32 s41, 0x10000
	v_lshl_add_u64 v[2:3], v[0:1], 0, s[42:43]
	v_lshl_add_u64 v[4:5], v[146:147], 1, s[16:17]
	v_add_co_u32_e32 v0, vcc, s41, v0
	s_addc_u32 s15, s15, 0
	v_lshl_add_u64 v[4:5], v[4:5], 0, v[172:173]
	v_addc_co_u32_e32 v1, vcc, 0, v1, vcc
	s_add_u32 s14, s14, s18
	s_mov_b64 s[42:43], 0xc000
	global_load_dwordx4 v[40:43], v[0:1], off
	v_add_co_u32_e32 v0, vcc, s19, v4
	s_addc_u32 s15, s15, 0
	v_lshl_add_u64 v[48:49], v[4:5], 0, s[42:43]
	v_addc_co_u32_e32 v1, vcc, 0, v5, vcc
	v_mov_b32_e32 v177, v145
	global_load_dwordx4 v[4:7], v[0:1], off
	global_load_dwordx4 v[44:47], v[2:3], off offset:64
	s_nop 0
	global_load_dwordx4 v[0:3], v[48:49], off offset:64
	v_lshl_add_u64 v[48:49], v[148:149], 1, s[16:17]
	v_lshl_add_u64 v[50:51], v[150:151], 1, s[16:17]
	v_lshl_add_u64 v[192:193], s[14:15], 0, v[176:177]
	s_lshl_b64 s[0:1], s[0:1], 2
	v_readlane_b32 s14, v253, 40
	global_load_ushort v175, v[48:49], off
	global_load_ushort v52, v[48:49], off offset:256
	global_load_ushort v53, v[48:49], off offset:512
	global_load_ushort v173, v[48:49], off offset:768
	global_load_ushort v171, v[48:49], off offset:32
	global_load_ushort v54, v[50:51], off offset:256
	global_load_ushort v55, v[50:51], off offset:512
	global_load_ushort v214, v[50:51], off offset:768
	global_load_ushort v213, v[48:49], off offset:64
	v_lshl_add_u64 v[50:51], v[152:153], 1, s[16:17]
	s_add_u32 s0, s14, s0
	v_readlane_b32 s14, v253, 41
	global_load_ushort v56, v[50:51], off offset:256
	global_load_ushort v57, v[50:51], off offset:512
	global_load_ushort v216, v[50:51], off offset:768
	global_load_ushort v215, v[48:49], off offset:96
	v_lshl_add_u64 v[48:49], v[154:155], 1, s[16:17]
	s_addc_u32 s1, s14, s1
	global_load_ushort v50, v[48:49], off offset:256
	global_load_ushort v51, v[48:49], off offset:512
	global_load_ushort v217, v[48:49], off offset:768
	global_load_dword v194, v145, s[0:1]
	s_cmp_lt_u32 s37, 32
	v_mov_b32_e32 v48, 0
	s_mov_b32 s40, 0
	s_cselect_b64 vcc, -1, 0
	v_mov_b32_e32 v177, v203
	v_mov_b32_e32 v49, v48
	v_mov_b32_e32 v58, v48
	v_mov_b32_e32 v59, v48
	v_mov_b32_e32 v60, v48
	v_mov_b32_e32 v61, v48
	v_mov_b32_e32 v62, v48
	v_mov_b32_e32 v63, v48
	v_mov_b32_e32 v64, v48
	v_mov_b32_e32 v65, v48
	v_mov_b32_e32 v66, v48
	v_mov_b32_e32 v67, v48
	v_mov_b32_e32 v68, v48
	v_mov_b32_e32 v69, v48
	v_mov_b32_e32 v70, v48
	v_mov_b32_e32 v71, v48
	v_mov_b32_e32 v76, v48
	v_mov_b32_e32 v77, v48
	v_mov_b32_e32 v78, v48
	v_mov_b32_e32 v79, v48
	v_mov_b32_e32 v72, v48
	v_mov_b32_e32 v73, v48
	v_mov_b32_e32 v74, v48
	v_mov_b32_e32 v75, v48
	s_waitcnt lgkmcnt(0)
	s_barrier
; #define LAS __attribute__((address_space(3)))
; __device__ __forceinline__ unsigned f2bf(float f) { return pk2(f, f) & 0xffffu; }
; __device__ __forceinline__ void gdn_scan_full(const bf16* CHUNK, const float* CD, bf16* OG, LAS unsigned char* lds, int item, int tid, int wave, int lane) {
;     ...
;         f32x4 wsum[4], os[4];
; #pragma unroll
;         for (int t = 0; t < 4; ++t) { wsum[t] = (f32x4){0.f, 0.f, 0.f, 0.f}; os[t] = (f32x4){0.f, 0.f, 0.f, 0.f}; }
; #pragma unroll
;         for (int t = 0; t < 4; ++t)
; #pragma unroll
;             for (int s = 0; s < 4; ++s) { const bf16x8_t sf = *(const LAS bf16x8_t*)(Sb + (64 * ng + 16 * t + ql) * 136 + 32 * s + 8 * gq);
;                 wsum[t] = __builtin_amdgcn_mfma_f32_16x16x32_bf16(wf[s], sf, wsum[t], 0, 0, 0); os[t] = __builtin_amdgcn_mfma_f32_16x16x32_bf16(qf[s], sf, os[t], 0, 0, 0); }
; #pragma unroll
;         for (int t = 0; t < 4; ++t) { s16x4_t vn;
; #pragma unroll
;             for (int j = 0; j < 4; ++j) vn[j] = (short)f2bf(__uint_as_float((unsigned)uu[t * 4 + j] << 16) - wsum[t][j]);
;             *(LAS s16x4_t*)(Vn + (64 * ng + 16 * t + ql) * 72 + 16 * mt + 4 * gq) = vn; }
	s_waitcnt vmcnt(14)
	v_perm_b32 v228, v53, v52, s20
	s_waitcnt vmcnt(10)
	v_perm_b32 v227, v55, v54, s20
	v_mov_b32_e32 v52, v48
	v_mov_b32_e32 v53, v48
	v_mov_b32_e32 v54, v48
	s_waitcnt vmcnt(6)
	v_perm_b32 v226, v57, v56, s20
	v_mov_b32_e32 v55, v48
	v_mov_b32_e32 v56, v48
	v_mov_b32_e32 v57, v48
	s_waitcnt vmcnt(2)
	v_perm_b32 v144, v51, v50, s20
	v_mov_b32_e32 v50, v48
	v_mov_b32_e32 v51, v48
	s_waitcnt vmcnt(0)
	v_mbcnt_lo_u32_b32 v196, -1, 0
	v_mbcnt_hi_u32_b32 v196, -1, v196
	v_and_b32_e32 v250, 15, v196
	v_lshrrev_b32_e32 v251, 4, v196
	v_lshrrev_b32_e32 v252, 3, v250
	v_and_b32_e32 v97, 7, v250
	v_lshrrev_b32_e32 v109, 1, v97
	v_and_b32_e32 v97, 1, v97
	v_lshlrev_b32_e32 v97, 4, v97
	v_mov_b32_e32 v213, 0xbf80
	v_lshlrev_b32_e32 v213, v97, v213
	v_xor_b32_e32 v252, v251, v252
	v_xor_b32_e32 v251, 2, v252
	v_xor_b32_e32 v97, 0, v109
	v_or_b32_e32 v97, v97, v252
	v_cmp_eq_u32_e64 s[0:1], 0, v97
	s_nop 1
	v_cndmask_b32_e64 v222, 0, v213, s[0:1]
	v_xor_b32_e32 v97, 1, v109
	v_or_b32_e32 v97, v97, v252
	v_cmp_eq_u32_e64 s[0:1], 0, v97
	s_nop 1
	v_cndmask_b32_e64 v223, 0, v213, s[0:1]
	v_xor_b32_e32 v97, 2, v109
	v_or_b32_e32 v97, v97, v252
	v_cmp_eq_u32_e64 s[0:1], 0, v97
	s_nop 1
	v_cndmask_b32_e64 v224, 0, v213, s[0:1]
	v_xor_b32_e32 v97, 3, v109
	v_or_b32_e32 v97, v97, v252
	v_cmp_eq_u32_e64 s[0:1], 0, v97
	s_nop 1
	v_cndmask_b32_e64 v225, 0, v213, s[0:1]
	v_xor_b32_e32 v97, 0, v109
	v_or_b32_e32 v97, v97, v251
	v_cmp_eq_u32_e64 s[0:1], 0, v97
	s_nop 1
	v_cndmask_b32_e64 v226, 0, v213, s[0:1]
	v_xor_b32_e32 v97, 1, v109
	v_or_b32_e32 v97, v97, v251
	v_cmp_eq_u32_e64 s[0:1], 0, v97
	s_nop 1
	v_cndmask_b32_e64 v227, 0, v213, s[0:1]
	v_xor_b32_e32 v97, 2, v109
	v_or_b32_e32 v97, v97, v251
	v_cmp_eq_u32_e64 s[0:1], 0, v97
	s_nop 1
	v_cndmask_b32_e64 v228, 0, v213, s[0:1]
	v_xor_b32_e32 v97, 3, v109
	v_or_b32_e32 v97, v97, v251
	v_cmp_eq_u32_e64 s[0:1], 0, v97
	s_nop 1
	v_cndmask_b32_e64 v229, 0, v213, s[0:1]
	s_lshr_b32 s0, s78, 2
	s_xor_b32 s0, s0, 1
	s_mulk_i32 s0, 0x2400
	v_add_u32_e32 v213, s0, v207
	s_lshr_b32 s98, s78, 2
	s_lshl_b32 s98, s98, 7
	s_add_u32 s98, s98, s35
	s_add_u32 s0, s28, s98
	s_addc_u32 s1, s29, 0
	s_sub_u32 s0, s0, s12
	s_subb_u32 s1, s1, s13
	v_lshl_add_u64 v[246:247], s[0:1], 0, v[186:187]
	global_load_dwordx4 v[214:217], v[246:247], off
	global_load_dwordx4 v[218:221], v[246:247], off offset:64
	s_waitcnt vmcnt(0)
.LBB0_367:
	v_add_u32_e32 v108, v195, v197
	v_add_u32_e32 v104, v195, v198
	v_add_u32_e32 v105, v169, v197
	v_add_u32_e32 v96, v169, v198
	ds_read_b128 v[80:83], v205
	ds_read_b128 v[84:87], v205 offset:64
	ds_read_b128 v[88:91], v205 offset:128
	ds_read_b128 v[92:95], v205 offset:192
	ds_read_b128 v[100:103], v205 offset:4352
	ds_read_b128 v[112:115], v205 offset:4416
	ds_read_b128 v[116:119], v205 offset:4480
	ds_read_b128 v[120:123], v205 offset:4544
	s_waitcnt lgkmcnt(7)
	v_mfma_f32_16x16x32_bf16 v[124:127], v[24:27], v[80:83], 0
	v_mul_f32_e32 v72, v194, v72
	v_mfma_f32_16x16x32_bf16 v[230:233], v[80:83], v[16:19], 0
	v_mul_f32_e32 v73, v194, v73
	ds_read_b128 v[80:83], v205 offset:8704
	s_waitcnt lgkmcnt(7)
	v_mfma_f32_16x16x32_bf16 v[124:127], v[28:31], v[84:87], v[124:127]
	v_mul_f32_e32 v74, v194, v74
	v_mfma_f32_16x16x32_bf16 v[230:233], v[84:87], v[12:15], v[230:233]
	v_mul_f32_e32 v75, v194, v75
	ds_read_b128 v[84:87], v205 offset:8768
	s_waitcnt lgkmcnt(7)
	v_mfma_f32_16x16x32_bf16 v[124:127], v[36:39], v[88:91], v[124:127]
	v_mul_f32_e32 v76, v194, v76
	v_mfma_f32_16x16x32_bf16 v[230:233], v[88:91], v[8:11], v[230:233]
	v_mul_f32_e32 v77, v194, v77
	ds_read_b128 v[88:91], v205 offset:8832
	s_waitcnt lgkmcnt(7)
	v_mfma_f32_16x16x32_bf16 v[124:127], v[32:35], v[92:95], v[124:127]
	v_mul_f32_e32 v78, v194, v78
	v_mfma_f32_16x16x32_bf16 v[230:233], v[92:95], v[20:23], v[230:233]
	v_mul_f32_e32 v79, v194, v79
	ds_read_b128 v[92:95], v205 offset:8896
	v_mfma_f32_16x16x32_bf16 v[124:127], v[214:217], v[222:225], v[124:127]
	s_waitcnt lgkmcnt(7)
	v_mfma_f32_16x16x32_bf16 v[128:131], v[24:27], v[100:103], 0
	v_mul_f32_e32 v68, v194, v68
	v_mfma_f32_16x16x32_bf16 v[234:237], v[100:103], v[16:19], 0
	v_mul_f32_e32 v69, v194, v69
	ds_read_b128 v[100:103], v206
	s_nop 1
	v_cvt_pk_bf16_f32 v98, -v124, -v125
	v_cvt_pk_bf16_f32 v99, -v126, -v127
	s_waitcnt lgkmcnt(7)
	v_mfma_f32_16x16x32_bf16 v[128:131], v[28:31], v[112:115], v[128:131]
	v_mul_f32_e32 v70, v194, v70
	v_mfma_f32_16x16x32_bf16 v[234:237], v[112:115], v[12:15], v[234:237]
	v_mul_f32_e32 v71, v194, v71
	ds_read_b128 v[112:115], v206 offset:64
	ds_write_b64 v108, v[98:99] offset:34816
	s_waitcnt lgkmcnt(8)
	v_mfma_f32_16x16x32_bf16 v[128:131], v[36:39], v[116:119], v[128:131]
	v_mul_f32_e32 v64, v194, v64
	v_mfma_f32_16x16x32_bf16 v[234:237], v[116:119], v[8:11], v[234:237]
	v_mul_f32_e32 v65, v194, v65
	ds_read_b128 v[116:119], v206 offset:128
	s_waitcnt lgkmcnt(8)
	v_mfma_f32_16x16x32_bf16 v[128:131], v[32:35], v[120:123], v[128:131]
	v_mul_f32_e32 v66, v194, v66
	v_mfma_f32_16x16x32_bf16 v[234:237], v[120:123], v[20:23], v[234:237]
	v_mul_f32_e32 v67, v194, v67
	ds_read_b128 v[120:123], v206 offset:192
	v_mfma_f32_16x16x32_bf16 v[128:131], v[214:217], v[226:229], v[128:131]
	s_waitcnt lgkmcnt(8)
	v_mfma_f32_16x16x32_bf16 v[132:135], v[24:27], v[80:83], 0
	v_mul_f32_e32 v60, v194, v60
	v_mfma_f32_16x16x32_bf16 v[238:241], v[80:83], v[16:19], 0
	v_mul_f32_e32 v61, v194, v61
	s_nop 2
	v_cvt_pk_bf16_f32 v106, -v128, -v129
	v_cvt_pk_bf16_f32 v107, -v130, -v131
	s_waitcnt lgkmcnt(7)
	v_mfma_f32_16x16x32_bf16 v[132:135], v[28:31], v[84:87], v[132:135]
	v_mul_f32_e32 v62, v194, v62
	v_mfma_f32_16x16x32_bf16 v[238:241], v[84:87], v[12:15], v[238:241]
	v_mul_f32_e32 v63, v194, v63
	ds_write_b64 v108, v[106:107] offset:37120
	s_waitcnt lgkmcnt(7)
; #define LAS __attribute__((address_space(3)))
; __device__ __forceinline__ unsigned f2bf(float f) { return pk2(f, f) & 0xffffu; }
; __device__ __forceinline__ void gdn_scan_full(const bf16* CHUNK, const float* CD, bf16* OG, LAS unsigned char* lds, int item, int tid, int wave, int lane) {
;     ...
; #pragma unroll
;         for (int t = 0; t < 4; ++t)
; #pragma unroll
;             for (int s = 0; s < 2; ++s) { const bf16x8_t vf = *(const LAS bf16x8_t*)(Vn + (64 * ng + 16 * t + ql) * 72 + 32 * s + 8 * gq); os[t] = __builtin_amdgcn_mfma_f32_16x16x32_bf16(inf[s], vf, os[t], 0, 0, 0); }
; #pragma unroll
;         for (int j = 0; j < 4; ++j) { const int c = n * 64 + 16 * mt + 4 * gq + j; const int tok = d ? SEQ - 1 - c : c;
; #pragma unroll
;             for (int t = 0; t < 4; ++t) og[(size_t)tok * 2048 + 16 * t] = (bf16)f2bf(os[t][j]); }
; #pragma unroll
;         for (int t = 0; t < 8; ++t) S[t] = S[t] * cdv;
; #pragma unroll
;         for (int t = 0; t < 8; ++t)
; #pragma unroll
;             for (int s = 0; s < 2; ++s) { const bf16x8_t v0 = *(const LAS bf16x8_t*)(Vn + (16 * t + ql) * 72 + 32 * s + 8 * gq); S[t] = __builtin_amdgcn_mfma_f32_16x16x32_bf16(kf[s], v0, S[t], 0, 0, 0); }
	v_mfma_f32_16x16x32_bf16 v[132:135], v[36:39], v[88:91], v[132:135]
	v_mul_f32_e32 v56, v194, v56
	v_mfma_f32_16x16x32_bf16 v[238:241], v[88:91], v[8:11], v[238:241]
	v_mul_f32_e32 v57, v194, v57
	s_waitcnt lgkmcnt(6)
	v_mfma_f32_16x16x32_bf16 v[132:135], v[32:35], v[92:95], v[132:135]
	v_mul_f32_e32 v58, v194, v58
	v_mfma_f32_16x16x32_bf16 v[238:241], v[92:95], v[20:23], v[238:241]
	v_mul_f32_e32 v59, v194, v59
	v_mfma_f32_16x16x32_bf16 v[132:135], v[218:221], v[222:225], v[132:135]
	s_waitcnt lgkmcnt(5)
	v_mfma_f32_16x16x32_bf16 v[136:139], v[24:27], v[100:103], 0
	v_mul_f32_e32 v52, v194, v52
	v_mfma_f32_16x16x32_bf16 v[242:245], v[100:103], v[16:19], 0
	v_mul_f32_e32 v53, v194, v53
	s_nop 2
	v_cvt_pk_bf16_f32 v110, -v132, -v133
	v_cvt_pk_bf16_f32 v111, -v134, -v135
	s_waitcnt lgkmcnt(4)
	v_mfma_f32_16x16x32_bf16 v[136:139], v[28:31], v[112:115], v[136:139]
	v_mul_f32_e32 v54, v194, v54
	v_mfma_f32_16x16x32_bf16 v[242:245], v[112:115], v[12:15], v[242:245]
	v_mul_f32_e32 v55, v194, v55
	ds_write_b64 v108, v[110:111] offset:39424
	s_waitcnt lgkmcnt(3)
	v_mfma_f32_16x16x32_bf16 v[136:139], v[36:39], v[116:119], v[136:139]
	v_mul_f32_e32 v48, v194, v48
	v_mfma_f32_16x16x32_bf16 v[242:245], v[116:119], v[8:11], v[242:245]
	v_mul_f32_e32 v49, v194, v49
	s_waitcnt lgkmcnt(2)
	v_mfma_f32_16x16x32_bf16 v[136:139], v[32:35], v[120:123], v[136:139]
	v_mul_f32_e32 v50, v194, v50
	v_mfma_f32_16x16x32_bf16 v[242:245], v[120:123], v[20:23], v[242:245]
	v_mul_f32_e32 v51, v194, v51
	v_mfma_f32_16x16x32_bf16 v[136:139], v[218:221], v[226:229], v[136:139]
	s_add_u32 s0, s28, s21
	s_addc_u32 s1, s29, 0
	v_lshl_add_u64 v[246:247], s[0:1], 0, v[186:187]
	s_add_u32 s0, s28, s22
	s_addc_u32 s1, s29, 0
	v_lshl_add_u64 v[248:249], s[0:1], 0, v[186:187]
	s_nop 1
	v_cvt_pk_bf16_f32 v98, -v136, -v137
	v_cvt_pk_bf16_f32 v99, -v138, -v139
	ds_write_b64 v104, v[98:99] offset:34816
	global_load_dwordx4 v[24:27], v[246:247], off
	global_load_dwordx4 v[16:19], v[248:249], off
	global_load_dwordx4 v[28:31], v[246:247], off offset:64
	global_load_dwordx4 v[12:15], v[248:249], off offset:64
	global_load_dwordx4 v[36:39], v[246:247], off offset:128
	global_load_dwordx4 v[8:11], v[248:249], off offset:128
	global_load_dwordx4 v[32:35], v[246:247], off offset:192
	global_load_dwordx4 v[20:23], v[248:249], off offset:192
	s_add_u32 s0, s28, s98
	s_addc_u32 s1, s29, 0
	v_lshl_add_u64 v[246:247], s[0:1], 0, v[186:187]
	global_load_dwordx4 v[214:217], v[246:247], off
	global_load_dwordx4 v[218:221], v[246:247], off offset:64
	s_add_u32 s0, s28, s38
	s_addc_u32 s1, s29, s39
	s_nop 0
	global_load_dword v194, v145, s[0:1]
	s_add_u32 s38, s38, 4
	s_addc_u32 s39, s39, 0
	s_waitcnt lgkmcnt(0)
	s_barrier
	ds_read_b128 v[80:83], v105 offset:34816
	ds_read_b128 v[84:87], v105 offset:34880
	ds_read_b128 v[88:91], v105 offset:37120
	ds_read_b128 v[92:95], v105 offset:37184
	ds_read_b128 v[100:103], v105 offset:39424
	ds_read_b128 v[112:115], v105 offset:39488
	ds_read_b128 v[116:119], v96 offset:34816
	ds_read_b128 v[120:123], v96 offset:34880
	ds_read_b128 v[124:127], v213 offset:34816
	ds_read_b128 v[128:131], v213 offset:34880
	ds_read_b128 v[132:135], v213 offset:37120
	ds_read_b128 v[136:139], v213 offset:37184
	ds_read_b128 v[246:249], v213 offset:39424
	s_waitcnt vmcnt(17)
	s_waitcnt lgkmcnt(12)
	v_mfma_f32_16x16x32_bf16 v[230:233], v[80:83], v[40:43], v[230:233]
	s_waitcnt lgkmcnt(11)
	v_mfma_f32_16x16x32_bf16 v[230:233], v[84:87], v[44:47], v[230:233]
	s_waitcnt lgkmcnt(10)
	v_mfma_f32_16x16x32_bf16 v[234:237], v[88:91], v[40:43], v[234:237]
	s_waitcnt lgkmcnt(9)
	v_mfma_f32_16x16x32_bf16 v[234:237], v[92:95], v[44:47], v[234:237]
	s_waitcnt lgkmcnt(8)
	v_mfma_f32_16x16x32_bf16 v[238:241], v[100:103], v[40:43], v[238:241]
	s_waitcnt lgkmcnt(7)
	v_mfma_f32_16x16x32_bf16 v[238:241], v[112:115], v[44:47], v[238:241]
	s_waitcnt lgkmcnt(6)
	v_mfma_f32_16x16x32_bf16 v[242:245], v[116:119], v[40:43], v[242:245]
	s_waitcnt lgkmcnt(5)
	v_mfma_f32_16x16x32_bf16 v[242:245], v[120:123], v[44:47], v[242:245]
	s_add_u32 s0, s28, s23
	s_addc_u32 s1, s29, 0
	v_lshl_add_u64 v[110:111], s[0:1], 0, v[190:191]
	global_load_dwordx4 v[40:43], v[110:111], off
	global_load_dwordx4 v[44:47], v[110:111], off offset:64
	v_mbcnt_lo_u32_b32 v196, -1, 0
	v_mbcnt_hi_u32_b32 v196, -1, v196
	v_and_b32_e32 v250, 15, v196
	v_lshrrev_b32_e32 v251, 2, v196
	v_and_b32_e32 v251, 12, v251
	v_sub_u32_e32 v251, v251, v250
	v_add_u32_e32 v252, s40, v141
	v_sub_u32_e32 v252, v252, v251
	v_add3_u32 v97, v177, v251, 3
	v_cndmask_b32_e32 v97, v97, v252, vcc
	v_lshlrev_b32_e32 v97, 12, v97
	v_lshl_add_u32 v109, v251, 1, v97
	v_add_u32_e32 v144, 64, v109
	v_lshl_add_u64 v[98:99], v[192:193], 0, v[144:145]
	v_cvt_pk_bf16_f32 v106, v230, v231
	v_cvt_pk_bf16_f32 v107, v232, v233
	global_store_dwordx2 v[98:99], v[106:107], off offset:-64
	v_cvt_pk_bf16_f32 v110, v234, v235
	v_cvt_pk_bf16_f32 v111, v236, v237
	global_store_dwordx2 v[98:99], v[110:111], off offset:-32
	v_cvt_pk_bf16_f32 v106, v238, v239
	v_cvt_pk_bf16_f32 v107, v240, v241
	global_store_dwordx2 v[98:99], v[106:107], off offset:0
	v_cvt_pk_bf16_f32 v110, v242, v243
	v_cvt_pk_bf16_f32 v111, v244, v245
	global_store_dwordx2 v[98:99], v[110:111], off offset:32
	ds_read_b128 v[230:233], v213 offset:39488
	ds_read_b128 v[234:237], v213 offset:41728
	ds_read_b128 v[238:241], v213 offset:41792
	s_add_i32 s40, s40, 64
	v_subrev_u32_e32 v177, 64, v177
	s_waitcnt vmcnt(17)
	s_cmp_lt_u32 s78, 4
	s_cbranch_scc0 .Lscan_c_ng1
	v_mfma_f32_16x16x32_bf16 v[72:75], v[4:7], v[80:83], v[72:75]
	v_mfma_f32_16x16x32_bf16 v[72:75], v[0:3], v[84:87], v[72:75]
	v_mfma_f32_16x16x32_bf16 v[76:79], v[4:7], v[88:91], v[76:79]
	v_mfma_f32_16x16x32_bf16 v[76:79], v[0:3], v[92:95], v[76:79]
	v_mfma_f32_16x16x32_bf16 v[68:71], v[4:7], v[100:103], v[68:71]
	v_mfma_f32_16x16x32_bf16 v[68:71], v[0:3], v[112:115], v[68:71]
	v_mfma_f32_16x16x32_bf16 v[64:67], v[4:7], v[116:119], v[64:67]
	v_mfma_f32_16x16x32_bf16 v[64:67], v[0:3], v[120:123], v[64:67]
	s_waitcnt lgkmcnt(7)
	v_mfma_f32_16x16x32_bf16 v[60:63], v[4:7], v[124:127], v[60:63]
	s_waitcnt lgkmcnt(6)
	v_mfma_f32_16x16x32_bf16 v[60:63], v[0:3], v[128:131], v[60:63]
	s_waitcnt lgkmcnt(5)
	v_mfma_f32_16x16x32_bf16 v[56:59], v[4:7], v[132:135], v[56:59]
	s_waitcnt lgkmcnt(4)
	v_mfma_f32_16x16x32_bf16 v[56:59], v[0:3], v[136:139], v[56:59]
	s_waitcnt lgkmcnt(3)
	v_mfma_f32_16x16x32_bf16 v[52:55], v[4:7], v[246:249], v[52:55]
	s_waitcnt lgkmcnt(2)
	v_mfma_f32_16x16x32_bf16 v[52:55], v[0:3], v[230:233], v[52:55]
	s_waitcnt lgkmcnt(1)
	v_mfma_f32_16x16x32_bf16 v[48:51], v[4:7], v[234:237], v[48:51]
	s_waitcnt lgkmcnt(0)
	v_mfma_f32_16x16x32_bf16 v[48:51], v[0:3], v[238:241], v[48:51]
	s_branch .Lscan_c_join
; #define LAS __attribute__((address_space(3)))
; __device__ __forceinline__ unsigned f2bf(float f) { return pk2(f, f) & 0xffffu; }
; __device__ __forceinline__ void gdn_scan_full(const bf16* CHUNK, const float* CD, bf16* OG, LAS unsigned char* lds, int item, int tid, int wave, int lane) {
;     ...
;         for (int t = 0; t < 4; ++t)
; #pragma unroll
;             for (int s = 0; s < 4; ++s) { const bf16x8_t sf = *(const LAS bf16x8_t*)(Sb + (64 * ng + 16 * t + ql) * 136 + 32 * s + 8 * gq);
;                 wsum[t] = __builtin_amdgcn_mfma_f32_16x16x32_bf16(wf[s], sf, wsum[t], 0, 0, 0); os[t] = __builtin_amdgcn_mfma_f32_16x16x32_bf16(qf[s], sf, os[t], 0, 0, 0); }
; #pragma unroll
;         for (int t = 0; t < 4; ++t) { s16x4_t vn;
; #pragma unroll
;             for (int j = 0; j < 4; ++j) vn[j] = (short)f2bf(__uint_as_float((unsigned)uu[t * 4 + j] << 16) - wsum[t][j]);
;             *(LAS s16x4_t*)(Vn + (64 * ng + 16 * t + ql) * 72 + 16 * mt + 4 * gq) = vn; }
;     ...
;         for (int t = 0; t < 8; ++t) S[t] = S[t] * cdv;
; #pragma unroll
;         for (int t = 0; t < 8; ++t)
; #pragma unroll
;             for (int s = 0; s < 2; ++s) { const bf16x8_t v0 = *(const LAS bf16x8_t*)(Vn + (16 * t + ql) * 72 + 32 * s + 8 * gq); S[t] = __builtin_amdgcn_mfma_f32_16x16x32_bf16(kf[s], v0, S[t], 0, 0, 0); }
; #pragma unroll
;         for (int t = 0; t < 8; ++t) { s16x4_t p;
; #pragma unroll
;             for (int j = 0; j < 4; ++j) p[j] = (short)f2bf(S[t][j]);
;             *(LAS s16x4_t*)(Sb + (16 * t + ql) * 136 + 16 * wave + 4 * gq) = p; }
.Lscan_c_ng1:
	v_mfma_f32_16x16x32_bf16 v[60:63], v[4:7], v[80:83], v[60:63]
	v_mfma_f32_16x16x32_bf16 v[60:63], v[0:3], v[84:87], v[60:63]
	v_mfma_f32_16x16x32_bf16 v[56:59], v[4:7], v[88:91], v[56:59]
	v_mfma_f32_16x16x32_bf16 v[56:59], v[0:3], v[92:95], v[56:59]
	v_mfma_f32_16x16x32_bf16 v[52:55], v[4:7], v[100:103], v[52:55]
	v_mfma_f32_16x16x32_bf16 v[52:55], v[0:3], v[112:115], v[52:55]
	v_mfma_f32_16x16x32_bf16 v[48:51], v[4:7], v[116:119], v[48:51]
	v_mfma_f32_16x16x32_bf16 v[48:51], v[0:3], v[120:123], v[48:51]
	s_waitcnt lgkmcnt(7)
	v_mfma_f32_16x16x32_bf16 v[72:75], v[4:7], v[124:127], v[72:75]
	s_waitcnt lgkmcnt(6)
	v_mfma_f32_16x16x32_bf16 v[72:75], v[0:3], v[128:131], v[72:75]
	s_waitcnt lgkmcnt(5)
	v_mfma_f32_16x16x32_bf16 v[76:79], v[4:7], v[132:135], v[76:79]
	s_waitcnt lgkmcnt(4)
	v_mfma_f32_16x16x32_bf16 v[76:79], v[0:3], v[136:139], v[76:79]
	s_waitcnt lgkmcnt(3)
	v_mfma_f32_16x16x32_bf16 v[68:71], v[4:7], v[246:249], v[68:71]
	s_waitcnt lgkmcnt(2)
	v_mfma_f32_16x16x32_bf16 v[68:71], v[0:3], v[230:233], v[68:71]
	s_waitcnt lgkmcnt(1)
	v_mfma_f32_16x16x32_bf16 v[64:67], v[4:7], v[234:237], v[64:67]
	s_waitcnt lgkmcnt(0)
	v_mfma_f32_16x16x32_bf16 v[64:67], v[0:3], v[238:241], v[64:67]
.Lscan_c_join:
	s_add_u32 s0, s28, s34
	s_addc_u32 s1, s29, 0
	v_lshl_add_u64 v[250:251], s[0:1], 0, v[188:189]
	global_load_dwordx4 v[4:7], v[250:251], off
	global_load_dwordx4 v[0:3], v[250:251], off offset:64
	v_lshl_add_u64 v[178:179], v[178:179], 0, s[12:13]
	v_lshl_add_u64 v[180:181], v[180:181], 0, s[12:13]
	v_lshl_add_u64 v[182:183], v[182:183], 0, s[12:13]
	v_lshl_add_u64 v[184:185], v[184:185], 0, s[12:13]
	v_lshl_add_u64 v[186:187], v[186:187], 0, s[12:13]
	v_lshl_add_u64 v[188:189], v[188:189], 0, s[12:13]
	v_lshl_add_u64 v[190:191], v[190:191], 0, s[12:13]
	v_cvt_pk_bf16_f32 v98, v72, v73
	v_cvt_pk_bf16_f32 v99, v74, v75
	ds_write_b64 v210, v[98:99]
	v_cvt_pk_bf16_f32 v106, v76, v77
	v_cvt_pk_bf16_f32 v107, v78, v79
	ds_write_b64 v210, v[106:107] offset:4352
	v_cvt_pk_bf16_f32 v98, v68, v69
	v_cvt_pk_bf16_f32 v99, v70, v71
	ds_write_b64 v210, v[98:99] offset:8704
	v_cvt_pk_bf16_f32 v106, v64, v65
	v_cvt_pk_bf16_f32 v107, v66, v67
	ds_write_b64 v211, v[106:107]
	v_cvt_pk_bf16_f32 v98, v60, v61
	v_cvt_pk_bf16_f32 v99, v62, v63
	ds_write_b64 v210, v[98:99] offset:17408
	v_cvt_pk_bf16_f32 v106, v56, v57
	v_cvt_pk_bf16_f32 v107, v58, v59
	ds_write_b64 v210, v[106:107] offset:21760
	v_cvt_pk_bf16_f32 v98, v52, v53
	v_cvt_pk_bf16_f32 v99, v54, v55
	ds_write_b64 v210, v[98:99] offset:26112
	v_cvt_pk_bf16_f32 v106, v48, v49
	v_cvt_pk_bf16_f32 v107, v50, v51
	ds_write_b64 v212, v[106:107]
	s_waitcnt vmcnt(8)
	s_waitcnt lgkmcnt(0)
	s_barrier
	s_cmpk_lg_i32 s40, 0xfc0
	s_cbranch_scc1 .LBB0_367
	s_waitcnt vmcnt(0)
	s_add_u32 s0, s28, s35
	s_addc_u32 s1, s29, 0
	s_sub_u32 s0, s0, s12
	s_subb_u32 s1, s1, s13
	v_lshl_add_u64 v[246:247], s[0:1], 0, v[184:185]
	v_lshl_add_u64 v[248:249], s[0:1], 0, v[182:183]
	v_lshl_add_u64 v[98:99], s[0:1], 0, v[180:181]
	v_lshl_add_u64 v[106:107], s[0:1], 0, v[178:179]
	global_load_ushort v175, v[246:247], off
	global_load_ushort v219, v[246:247], off offset:256
	global_load_ushort v218, v[246:247], off offset:512
	global_load_ushort v173, v[246:247], off offset:768
	global_load_ushort v171, v[246:247], off offset:32
	global_load_ushort v221, v[248:249], off offset:256
	global_load_ushort v220, v[248:249], off offset:512
	global_load_ushort v214, v[248:249], off offset:768
	global_load_ushort v213, v[246:247], off offset:64
	global_load_ushort v223, v[98:99], off offset:256
	global_load_ushort v222, v[98:99], off offset:512
	global_load_ushort v216, v[98:99], off offset:768
	global_load_ushort v215, v[246:247], off offset:96
	global_load_ushort v225, v[106:107], off offset:256
	global_load_ushort v224, v[106:107], off offset:512
	global_load_ushort v217, v[106:107], off offset:768
	s_waitcnt vmcnt(0)
	ds_read_b128 v[80:83], v205
	ds_read_b128 v[84:87], v205 offset:64
	v_lshlrev_b32_e32 v103, 16, v219
	v_lshlrev_b32_e32 v102, 16, v175
	s_add_i32 s37, s37, s74
	s_waitcnt lgkmcnt(1)
	v_mfma_f32_16x16x32_bf16 v[88:91], v[24:27], v[80:83], 0
	s_add_i32 s36, s36, s74
	s_cmp_gt_i32 s37, 63
	v_mfma_f32_16x16x32_bf16 v[80:83], v[16:19], v[80:83], 0
	s_waitcnt lgkmcnt(0)
	v_mfma_f32_16x16x32_bf16 v[88:91], v[28:31], v[84:87], v[88:91]
	v_mfma_f32_16x16x32_bf16 v[80:83], v[12:15], v[84:87], v[80:83]
	ds_read_b128 v[84:87], v205 offset:128
	ds_read_b128 v[92:95], v205 offset:192
	s_waitcnt lgkmcnt(1)
	v_mfma_f32_16x16x32_bf16 v[88:91], v[36:39], v[84:87], v[88:91]
	v_mfma_f32_16x16x32_bf16 v[80:83], v[8:11], v[84:87], v[80:83]
	s_waitcnt lgkmcnt(0)
	v_mfma_f32_16x16x32_bf16 v[84:87], v[32:35], v[92:95], v[88:91]
	v_mfma_f32_16x16x32_bf16 v[80:83], v[20:23], v[92:95], v[80:83]
	s_nop 3
	ds_read_b128 v[88:91], v205 offset:4352
	ds_read_b128 v[92:95], v205 offset:4416
	s_nop 0
	v_pk_add_f32 v[84:85], v[102:103], v[84:85] neg_lo:[0,1] neg_hi:[0,1]
	v_lshlrev_b32_e32 v103, 16, v173
	s_waitcnt lgkmcnt(1)
	v_mfma_f32_16x16x32_bf16 v[98:101], v[24:27], v[88:91], 0
	v_lshlrev_b32_e32 v102, 16, v218
	v_pk_add_f32 v[86:87], v[102:103], v[86:87] neg_lo:[0,1] neg_hi:[0,1]
	v_cvt_pk_bf16_f32 v84, v84, v85
	v_mfma_f32_16x16x32_bf16 v[88:91], v[16:19], v[88:91], 0
	v_cvt_pk_bf16_f32 v85, v86, v87
	v_lshlrev_b32_e32 v103, 16, v214
	v_lshlrev_b32_e32 v102, 16, v220
	s_waitcnt lgkmcnt(0)
	v_mfma_f32_16x16x32_bf16 v[98:101], v[28:31], v[92:95], v[98:101]
	v_mfma_f32_16x16x32_bf16 v[88:91], v[12:15], v[92:95], v[88:91]
	ds_read_b128 v[92:95], v205 offset:4480
	ds_read_b128 v[110:113], v205 offset:4544
	s_waitcnt lgkmcnt(1)
; #define LAS __attribute__((address_space(3)))
; #define LDS_BARRIER() do { asm volatile("s_waitcnt lgkmcnt(0)" ::: "memory"); __builtin_amdgcn_s_barrier(); asm volatile("" ::: "memory"); } while (0)
; __device__ __forceinline__ unsigned f2bf(float f) { return pk2(f, f) & 0xffffu; }
; __device__ __forceinline__ void gdn_scan_full(const bf16* CHUNK, const float* CD, bf16* OG, LAS unsigned char* lds, int item, int tid, int wave, int lane) {
;     ...
;         for (int t = 0; t < 4; ++t)
; #pragma unroll
;             for (int s = 0; s < 4; ++s) { const bf16x8_t sf = *(const LAS bf16x8_t*)(Sb + (64 * ng + 16 * t + ql) * 136 + 32 * s + 8 * gq);
;                 wsum[t] = __builtin_amdgcn_mfma_f32_16x16x32_bf16(wf[s], sf, wsum[t], 0, 0, 0); os[t] = __builtin_amdgcn_mfma_f32_16x16x32_bf16(qf[s], sf, os[t], 0, 0, 0); }
; #pragma unroll
;         for (int t = 0; t < 4; ++t) { s16x4_t vn;
; #pragma unroll
;             for (int j = 0; j < 4; ++j) vn[j] = (short)f2bf(__uint_as_float((unsigned)uu[t * 4 + j] << 16) - wsum[t][j]);
;             *(LAS s16x4_t*)(Vn + (64 * ng + 16 * t + ql) * 72 + 16 * mt + 4 * gq) = vn; }
;         LDS_BARRIER();
	v_mfma_f32_16x16x32_bf16 v[98:101], v[36:39], v[92:95], v[98:101]
	v_mfma_f32_16x16x32_bf16 v[88:91], v[8:11], v[92:95], v[88:91]
	s_waitcnt lgkmcnt(0)
	v_mfma_f32_16x16x32_bf16 v[92:95], v[32:35], v[110:113], v[98:101]
	v_mfma_f32_16x16x32_bf16 v[88:91], v[20:23], v[110:113], v[88:91]
	s_nop 3
	ds_read_b128 v[98:101], v205 offset:8704
	ds_read_b128 v[110:113], v205 offset:8768
	ds_read_b128 v[118:121], v205 offset:8832
	ds_read_b128 v[122:125], v205 offset:8896
	ds_read_b128 v[126:129], v206
	ds_read_b128 v[130:133], v206 offset:64
	ds_read_b128 v[134:137], v206 offset:128
	ds_read_b128 v[178:181], v206 offset:192
	s_waitcnt lgkmcnt(7)
	v_mfma_f32_16x16x32_bf16 v[114:117], v[24:27], v[98:101], 0
	ds_write_b64 v108, v[84:85] offset:34816
	v_pk_add_f32 v[94:95], v[102:103], v[94:95] neg_lo:[0,1] neg_hi:[0,1]
	v_mfma_f32_16x16x32_bf16 v[98:101], v[16:19], v[98:101], 0
	s_waitcnt lgkmcnt(4)
	v_mfma_f32_16x16x32_bf16 v[24:27], v[24:27], v[126:129], 0
	v_mfma_f32_16x16x32_bf16 v[114:117], v[28:31], v[110:113], v[114:117]
	v_mfma_f32_16x16x32_bf16 v[98:101], v[12:15], v[110:113], v[98:101]
	s_waitcnt lgkmcnt(3)
	v_mfma_f32_16x16x32_bf16 v[24:27], v[28:31], v[130:133], v[24:27]
	v_lshlrev_b32_e32 v31, 16, v216
	v_lshlrev_b32_e32 v30, 16, v222
	v_mfma_f32_16x16x32_bf16 v[110:113], v[36:39], v[118:121], v[114:117]
	v_mfma_f32_16x16x32_bf16 v[84:87], v[8:11], v[118:121], v[98:101]
	s_nop 2
	v_lshlrev_b32_e32 v99, 16, v221
	v_lshlrev_b32_e32 v98, 16, v171
	s_waitcnt lgkmcnt(2)
	v_mfma_f32_16x16x32_bf16 v[24:27], v[36:39], v[134:137], v[24:27]
	v_add_f32_e64 v92, v98, -v92
	v_add_f32_e64 v93, v99, -v93
	v_or_b32_e32 v36, 0xfc0, v141
	v_cvt_pk_bf16_f32 v92, v92, v93
	v_mfma_f32_16x16x32_bf16 v[98:101], v[32:35], v[122:125], v[110:113]
	v_cvt_pk_bf16_f32 v93, v94, v95
	ds_write_b64 v108, v[92:93] offset:37120
	v_lshlrev_b32_e32 v93, 16, v223
	v_lshlrev_b32_e32 v92, 16, v213
	s_waitcnt lgkmcnt(2)
	v_mfma_f32_16x16x32_bf16 v[24:27], v[32:35], v[178:181], v[24:27]
	s_nop 1
	v_add_f32_e64 v92, v92, -v98
	v_add_f32_e64 v93, v93, -v99
	v_pk_add_f32 v[30:31], v[30:31], v[100:101] neg_lo:[0,1] neg_hi:[0,1]
	v_cvt_pk_bf16_f32 v28, v92, v93
	v_mfma_f32_16x16x32_bf16 v[16:19], v[16:19], v[126:129], 0
	v_cvt_pk_bf16_f32 v29, v30, v31
	ds_write_b64 v108, v[28:29] offset:39424
	v_lshlrev_b32_e32 v29, 16, v225
	v_lshlrev_b32_e32 v28, 16, v215
	v_pk_add_f32 v[24:25], v[28:29], v[24:25] neg_lo:[0,1] neg_hi:[0,1]
	s_waitcnt vmcnt(17)
	v_lshlrev_b32_e32 v29, 16, v217
	v_lshlrev_b32_e32 v28, 16, v224
	v_mfma_f32_16x16x32_bf16 v[12:15], v[12:15], v[130:133], v[16:19]
	v_cvt_pk_bf16_f32 v24, v24, v25
	v_cndmask_b32_e32 v36, v199, v36, vcc
	v_lshlrev_b32_e32 v144, 12, v36
	v_pk_add_f32 v[16:17], v[28:29], v[26:27] neg_lo:[0,1] neg_hi:[0,1]
	v_mfma_f32_16x16x32_bf16 v[8:11], v[8:11], v[134:137], v[12:15]
	v_cvt_pk_bf16_f32 v25, v16, v17
	ds_write_b64 v104, v[24:25] offset:34816
	s_waitcnt lgkmcnt(0)
	s_barrier
; #define LAS __attribute__((address_space(3)))
; #define LDS_BARRIER() do { asm volatile("s_waitcnt lgkmcnt(0)" ::: "memory"); __builtin_amdgcn_s_barrier(); asm volatile("" ::: "memory"); } while (0)
; __device__ __forceinline__ unsigned f2bf(float f) { return pk2(f, f) & 0xffffu; }
; __device__ __forceinline__ void gdn_scan_full(const bf16* CHUNK, const float* CD, bf16* OG, LAS unsigned char* lds, int item, int tid, int wave, int lane) {
;     ...
; #pragma unroll
;         for (int t = 0; t < 4; ++t)
; #pragma unroll
;             for (int s = 0; s < 2; ++s) { const bf16x8_t vf = *(const LAS bf16x8_t*)(Vn + (64 * ng + 16 * t + ql) * 72 + 32 * s + 8 * gq); os[t] = __builtin_amdgcn_mfma_f32_16x16x32_bf16(inf[s], vf, os[t], 0, 0, 0); }
; #pragma unroll
;         for (int j = 0; j < 4; ++j) { const int c = n * 64 + 16 * mt + 4 * gq + j; const int tok = d ? SEQ - 1 - c : c;
; #pragma unroll
;             for (int t = 0; t < 4; ++t) og[(size_t)tok * 2048 + 16 * t] = (bf16)f2bf(os[t][j]); }
; #pragma unroll
;         for (int t = 0; t < 8; ++t) S[t] = S[t] * cdv;
; #pragma unroll
;         for (int t = 0; t < 8; ++t)
; #pragma unroll
;             for (int s = 0; s < 2; ++s) { const bf16x8_t v0 = *(const LAS bf16x8_t*)(Vn + (16 * t + ql) * 72 + 32 * s + 8 * gq); S[t] = __builtin_amdgcn_mfma_f32_16x16x32_bf16(kf[s], v0, S[t], 0, 0, 0); }
; #pragma unroll
;         for (int t = 0; t < 8; ++t) { s16x4_t p;
; #pragma unroll
;             for (int j = 0; j < 4; ++j) p[j] = (short)f2bf(S[t][j]);
;             *(LAS s16x4_t*)(Sb + (16 * t + ql) * 136 + 16 * wave + 4 * gq) = p; }
;         LDS_BARRIER();
	ds_read_b128 v[12:15], v105 offset:34816
	ds_read_b128 v[16:19], v105 offset:34880
	s_waitcnt lgkmcnt(1)
	v_mfma_f32_16x16x32_bf16 v[12:15], v[40:43], v[12:15], v[80:83]
	v_mfma_f32_16x16x32_bf16 v[84:87], v[20:23], v[122:125], v[84:87]
	v_mfma_f32_16x16x32_bf16 v[8:11], v[20:23], v[178:181], v[8:11]
	s_waitcnt lgkmcnt(0)
	v_mfma_f32_16x16x32_bf16 v[12:15], v[44:47], v[16:19], v[12:15]
	ds_read_b128 v[16:19], v105 offset:37120
	ds_read_b128 v[20:23], v105 offset:37184
	ds_read_b128 v[24:27], v105 offset:39424
	ds_read_b128 v[28:31], v105 offset:39488
	s_waitcnt lgkmcnt(3)
	v_mfma_f32_16x16x32_bf16 v[16:19], v[40:43], v[16:19], v[88:91]
	s_nop 1
	v_cvt_pk_bf16_f32 v12, v12, s0
	s_waitcnt lgkmcnt(2)
	v_mfma_f32_16x16x32_bf16 v[16:19], v[44:47], v[20:23], v[16:19]
	ds_read_b128 v[20:23], v96 offset:34816
	ds_read_b128 v[32:35], v96 offset:34880
	ds_read_b128 v[36:39], v207 offset:39488
	s_waitcnt lgkmcnt(2)
	v_mfma_f32_16x16x32_bf16 v[8:11], v[40:43], v[20:23], v[8:11]
	ds_read_b128 v[20:23], v207 offset:34880
	v_mfma_f32_16x16x32_bf16 v[24:27], v[40:43], v[24:27], v[84:87]
	ds_read_b128 v[40:43], v208 offset:34816
	s_waitcnt lgkmcnt(3)
	v_mfma_f32_16x16x32_bf16 v[8:11], v[44:47], v[32:35], v[8:11]
	ds_read_b128 v[32:35], v207 offset:39424
	v_mfma_f32_16x16x32_bf16 v[24:27], v[44:47], v[28:31], v[24:27]
	v_lshl_add_u64 v[28:29], v[192:193], 0, v[144:145]
	s_nop 4
	v_cvt_pk_bf16_f32 v8, v8, s0
	global_store_short v[28:29], v8, off offset:96
	v_or_b32_e32 v8, 0xfc1, v141
	global_store_short v[28:29], v12, off
	v_cvt_pk_bf16_f32 v12, v16, s0
	v_cndmask_b32_e32 v8, v200, v8, vcc
	global_store_short v[28:29], v12, off offset:32
	v_cvt_pk_bf16_f32 v12, v24, s0
	v_lshlrev_b32_e32 v144, 12, v8
	global_store_short v[28:29], v12, off offset:64
	v_cvt_pk_bf16_f32 v16, v13, s0
	v_lshl_add_u64 v[12:13], v[192:193], 0, v[144:145]
	v_cvt_pk_bf16_f32 v8, v17, s0
	global_store_short v[12:13], v8, off offset:32
	v_cvt_pk_bf16_f32 v8, v25, s0
	global_store_short v[12:13], v8, off offset:64
	v_cvt_pk_bf16_f32 v8, v9, s0
	global_store_short v[12:13], v8, off offset:96
	v_or_b32_e32 v8, 0xfc2, v141
	v_cndmask_b32_e32 v8, v201, v8, vcc
	v_lshlrev_b32_e32 v144, 12, v8
	global_store_short v[12:13], v16, off
	v_cvt_pk_bf16_f32 v12, v14, s0
	v_lshl_add_u64 v[8:9], v[192:193], 0, v[144:145]
	global_store_short v[8:9], v12, off
	v_cvt_pk_bf16_f32 v12, v18, s0
	global_store_short v[8:9], v12, off offset:32
	v_cvt_pk_bf16_f32 v12, v26, s0
	v_cvt_pk_bf16_f32 v10, v10, s0
	global_store_short v[8:9], v12, off offset:64
	global_store_short v[8:9], v10, off offset:96
	v_or_b32_e32 v8, 0xfc3, v141
	v_cndmask_b32_e32 v8, v202, v8, vcc
	v_lshlrev_b32_e32 v144, 12, v8
	v_cvt_pk_bf16_f32 v10, v15, s0
	v_lshl_add_u64 v[8:9], v[192:193], 0, v[144:145]
	global_store_short v[8:9], v10, off
	v_cvt_pk_bf16_f32 v10, v19, s0
	global_store_short v[8:9], v10, off offset:32
	v_cvt_pk_bf16_f32 v10, v27, s0
	ds_read_b128 v[12:15], v207 offset:34816
	ds_read_b128 v[24:27], v207 offset:37120
	ds_read_b128 v[28:31], v207 offset:37184
	global_store_short v[8:9], v10, off offset:64
	v_cvt_pk_bf16_f32 v10, v11, s0
	global_store_short v[8:9], v10, off offset:96
	s_waitcnt vmcnt(32)
	v_pk_mul_f32 v[10:11], v[194:195], v[74:75] op_sel_hi:[0,1]
	v_pk_mul_f32 v[8:9], v[194:195], v[72:73] op_sel_hi:[0,1]
	v_pk_mul_f32 v[18:19], v[194:195], v[78:79] op_sel_hi:[0,1]
	v_pk_mul_f32 v[16:17], v[194:195], v[76:77] op_sel_hi:[0,1]
	s_waitcnt lgkmcnt(2)
	v_mfma_f32_16x16x32_bf16 v[8:11], v[4:7], v[12:15], v[8:11]
	v_mul_f32_e64 v14, v194, v70
	v_mul_f32_e64 v15, v194, v71
	v_pk_mul_f32 v[12:13], v[194:195], v[68:69] op_sel_hi:[0,1]
	ds_read_b128 v[44:47], v208 offset:34880
	s_waitcnt lgkmcnt(2)
	v_mfma_f32_16x16x32_bf16 v[16:19], v[4:7], v[24:27], v[16:19]
	v_mul_f32_e64 v26, v194, v62
	v_mul_f32_e64 v27, v194, v63
	v_pk_mul_f32 v[24:25], v[194:195], v[60:61] op_sel_hi:[0,1]
	v_mfma_f32_16x16x32_bf16 v[12:15], v[4:7], v[32:35], v[12:15]
	v_mul_f32_e64 v34, v194, v54
	v_mul_f32_e64 v35, v194, v55
	v_pk_mul_f32 v[32:33], v[194:195], v[52:53] op_sel_hi:[0,1]
	v_mfma_f32_16x16x32_bf16 v[8:11], v[0:3], v[20:23], v[8:11]
	v_mul_f32_e64 v22, v194, v66
	v_mul_f32_e64 v23, v194, v67
	v_pk_mul_f32 v[20:21], v[194:195], v[64:65] op_sel_hi:[0,1]
	s_waitcnt lgkmcnt(1)
	v_mfma_f32_16x16x32_bf16 v[16:19], v[0:3], v[28:31], v[16:19]
	v_mul_f32_e64 v30, v194, v58
	v_mul_f32_e64 v31, v194, v59
	v_pk_mul_f32 v[28:29], v[194:195], v[56:57] op_sel_hi:[0,1]
	v_cvt_pk_bf16_f32 v11, v10, v11
	v_mfma_f32_16x16x32_bf16 v[12:15], v[0:3], v[36:39], v[12:15]
	v_mul_f32_e64 v38, v194, v50
	v_mul_f32_e64 v39, v194, v51
	v_pk_mul_f32 v[36:37], v[194:195], v[48:49] op_sel_hi:[0,1]
	v_cvt_pk_bf16_f32 v19, v18, v19
	v_mfma_f32_16x16x32_bf16 v[20:23], v[4:7], v[40:43], v[20:23]
	ds_read_b128 v[40:43], v207 offset:44032
	ds_read_b128 v[48:51], v207 offset:44096
	ds_read_b128 v[52:55], v207 offset:46336
	ds_read_b128 v[56:59], v207 offset:46400
	v_cvt_pk_bf16_f32 v18, v16, v17
	v_cvt_pk_bf16_f32 v10, v8, v9
	s_waitcnt lgkmcnt(4)
	v_mfma_f32_16x16x32_bf16 v[20:23], v[0:3], v[44:47], v[20:23]
	ds_read_b128 v[44:47], v207 offset:48640
	ds_read_b128 v[60:63], v207 offset:48704
	ds_read_b128 v[64:67], v209 offset:34816
	ds_read_b128 v[68:71], v209 offset:34880
	ds_write_b64 v210, v[18:19] offset:4352
	v_cvt_pk_bf16_f32 v15, v14, v15
	s_waitcnt lgkmcnt(8)
	v_mfma_f32_16x16x32_bf16 v[24:27], v[4:7], v[40:43], v[24:27]
	v_cvt_pk_bf16_f32 v14, v12, v13
	ds_write_b64 v210, v[10:11]
	ds_write_b64 v210, v[14:15] offset:8704
	s_waitcnt lgkmcnt(8)
	v_mfma_f32_16x16x32_bf16 v[16:19], v[4:7], v[52:55], v[28:31]
	v_mfma_f32_16x16x32_bf16 v[8:11], v[0:3], v[48:51], v[24:27]
	s_waitcnt lgkmcnt(7)
	v_mfma_f32_16x16x32_bf16 v[12:15], v[0:3], v[56:59], v[16:19]
	s_nop 4
	v_cvt_pk_bf16_f32 v17, v22, v23
	v_cvt_pk_bf16_f32 v16, v20, v21
	ds_write_b64 v211, v[16:17]
	s_waitcnt lgkmcnt(7)
	v_mfma_f32_16x16x32_bf16 v[16:19], v[4:7], v[44:47], v[32:35]
	v_cvt_pk_bf16_f32 v11, v10, v11
	v_cvt_pk_bf16_f32 v10, v8, v9
	ds_write_b64 v210, v[10:11] offset:17408
	s_waitcnt lgkmcnt(6)
	v_mfma_f32_16x16x32_bf16 v[4:7], v[4:7], v[64:67], v[36:39]
	v_cvt_pk_bf16_f32 v15, v14, v15
	v_cvt_pk_bf16_f32 v14, v12, v13
	ds_write_b64 v210, v[14:15] offset:21760
	v_mfma_f32_16x16x32_bf16 v[8:11], v[0:3], v[60:63], v[16:19]
	s_waitcnt lgkmcnt(6)
	v_mfma_f32_16x16x32_bf16 v[0:3], v[0:3], v[68:71], v[4:7]
	s_nop 5
	v_cvt_pk_bf16_f32 v11, v10, v11
	v_cvt_pk_bf16_f32 v10, v8, v9
	v_cvt_pk_bf16_f32 v3, v2, v3
	v_cvt_pk_bf16_f32 v2, v0, v1
	ds_write_b64 v210, v[10:11] offset:26112
	ds_write_b64 v212, v[2:3]
	s_waitcnt lgkmcnt(0)
	s_barrier
	s_waitcnt lgkmcnt(0)
	s_barrier
	s_cbranch_scc0 .LBB0_364
